# c20: dense attention staging waits count only the older landing set (vmcnt 3/2 instead of 1/0), younger K/V prefetch stays in flight
# speedup vs baseline: 1.0168x; 1.0168x over previous
; __device__ __forceinline__ unsigned pk2(float lo, float hi) { f32x2 v = {lo, hi}; bf16x2_t b = __builtin_convertvector(v, bf16x2_t); return __builtin_bit_cast(unsigned, b); }
; __device__ __forceinline__ v4i16 tr16(const unsigned char* p) { return __builtin_amdgcn_ds_read_tr16_b64_v4i16((LDSAS v4i16*)p); }
; __device__ __forceinline__ void at_ldv(bf16x8 (&v0)[4], bf16x8 (&v1)[4], const unsigned char* Vs, int lane) {
;     const int hi = lane >> 5;
;     const unsigned char* vb = Vs + ((lane >> 4) & 1) * 32 + (lane & 3) * 8 + (4 * hi + ((lane & 15) >> 2)) * 64;
; #pragma unroll
;     for (int s = 0; s < 4; ++s) {
;         v0[s] = cat8(tr16(vb + s * 1024), tr16(vb + s * 1024 + 512));
;         v1[s] = cat8(tr16(vb + 4096 + s * 1024), tr16(vb + 4096 + s * 1024 + 512));
;     }
; }
; __device__ __forceinline__ void at_pv2(f32x16& o0, f32x16& o1, const f32x16& p0, const f32x16& p1, const bf16x8 (&v0)[4], const bf16x8 (&v1)[4]) {
;     bf16x8 pa[4];
; #pragma unroll
;     for (int s = 0; s < 4; ++s) {
;         u32x4 pw;
;         if (s < 2) { pw.x = pk2(p0[8 * s + 0], p0[8 * s + 1]); pw.y = pk2(p0[8 * s + 2], p0[8 * s + 3]); pw.z = pk2(p0[8 * s + 4], p0[8 * s + 5]); pw.w = pk2(p0[8 * s + 6], p0[8 * s + 7]); }
;         else { const int q = s - 2; pw.x = pk2(p1[8 * q + 0], p1[8 * q + 1]); pw.y = pk2(p1[8 * q + 2], p1[8 * q + 3]); pw.z = pk2(p1[8 * q + 4], p1[8 * q + 5]); pw.w = pk2(p1[8 * q + 6], p1[8 * q + 7]); }
;         pa[s] = __builtin_bit_cast(bf16x8, pw);
;     }
;     __builtin_amdgcn_sched_barrier(0);
;     __builtin_amdgcn_s_setprio(1);
; #pragma unroll
;     for (int s = 0; s < 4; ++s) {
;         o0 = __builtin_amdgcn_mfma_f32_32x32x16_bf16(pa[s], v0[s], o0, 0, 0, 0);
;         o1 = __builtin_amdgcn_mfma_f32_32x32x16_bf16(pa[s], v1[s], o1, 0, 0, 0);
;     }
;     __builtin_amdgcn_s_setprio(0);
;     __builtin_amdgcn_sched_barrier(0);
; }
; __device__ void attn_a_item(const Params& p, int item, int l, unsigned char* smem) {
;     ...
;     __syncthreads();
;     ATA_LOAD(rkA, rvA, 0); ATA_LOAD(rkB, rvB, 1);
;     ATA_STORE(rkA, rvA, 0);
;     ATA_LOAD(rkA, rvA, 2);
;     __syncthreads();
;     for (int kt = 0; kt < NT; kt += 2) {
;         ATA_COMPUTE(0);
;         ATA_STORE(rkB, rvB, 1);
;         if (kt + 3 < NT) ATA_LOAD(rkB, rvB, kt + 3);
.LBB0_847:
	ds_read_b128 v[64:67], v80
	ds_read_b128 v[120:123], v80 offset:32
	ds_read_b128 v[124:127], v80 offset:4608
	ds_read_b128 v[128:131], v80 offset:4640
	ds_read_b128 v[132:135], v80 offset:64
	ds_read_b128 v[136:139], v80 offset:96
	ds_read_b128 v[140:143], v80 offset:4672
	ds_read_b128 v[144:147], v80 offset:4704
	s_setprio 1
	s_waitcnt lgkmcnt(7)
	v_mfma_f32_32x32x16_bf16 v[48:63], v[64:67], v[82:85], v[32:47]
	s_waitcnt lgkmcnt(5)
	v_mfma_f32_32x32x16_bf16 v[64:79], v[124:127], v[82:85], v[32:47]
	v_mfma_f32_32x32x16_bf16 v[48:63], v[120:123], v[86:89], v[48:63]
	s_waitcnt lgkmcnt(4)
	v_mfma_f32_32x32x16_bf16 v[64:79], v[128:131], v[86:89], v[64:79]
	s_waitcnt lgkmcnt(3)
	v_mfma_f32_32x32x16_bf16 v[48:63], v[132:135], v[90:93], v[48:63]
	s_waitcnt lgkmcnt(1)
	v_mfma_f32_32x32x16_bf16 v[64:79], v[140:143], v[90:93], v[64:79]
	v_mfma_f32_32x32x16_bf16 v[48:63], v[136:139], v[94:97], v[48:63]
	s_waitcnt lgkmcnt(0)
	v_mfma_f32_32x32x16_bf16 v[64:79], v[144:147], v[94:97], v[64:79]
	s_setprio 0
	ds_read_b64_tr_b16 v[158:159], v157 offset:9216
	ds_read_b64_tr_b16 v[160:161], v157 offset:9728
	ds_read_b64_tr_b16 v[162:163], v157 offset:10240
	ds_read_b64_tr_b16 v[164:165], v157 offset:10752
	ds_read_b64_tr_b16 v[166:167], v157 offset:13312
	ds_read_b64_tr_b16 v[168:169], v157 offset:13824
	ds_read_b64_tr_b16 v[170:171], v157 offset:14336
	ds_read_b64_tr_b16 v[172:173], v157 offset:14848
	ds_read_b64_tr_b16 v[174:175], v157 offset:11264
	ds_read_b64_tr_b16 v[176:177], v157 offset:11776
	ds_read_b64_tr_b16 v[180:181], v157 offset:12288
	ds_read_b64_tr_b16 v[182:183], v157 offset:12800
	ds_read_b64_tr_b16 v[184:185], v157 offset:15360
	ds_read_b64_tr_b16 v[186:187], v157 offset:15872
	ds_read_b64_tr_b16 v[188:189], v157 offset:16384
	ds_read_b64_tr_b16 v[190:191], v157 offset:16896
	v_exp_f32_e32 v150, v48
	v_exp_f32_e32 v136, v64
	v_exp_f32_e32 v151, v49
	v_exp_f32_e32 v137, v65
	v_exp_f32_e32 v148, v50
	v_exp_f32_e32 v146, v66
	v_exp_f32_e32 v149, v51
	v_exp_f32_e32 v147, v67
	v_exp_f32_e32 v142, v52
	v_exp_f32_e32 v128, v68
	v_exp_f32_e32 v143, v53
	v_exp_f32_e32 v129, v69
	v_exp_f32_e32 v144, v54
	v_exp_f32_e32 v140, v70
	v_exp_f32_e32 v145, v55
	v_exp_f32_e32 v141, v71
	v_exp_f32_e32 v134, v56
	v_exp_f32_e32 v122, v72
	v_exp_f32_e32 v135, v57
	v_exp_f32_e32 v123, v73
	v_exp_f32_e32 v138, v58
	v_exp_f32_e32 v132, v74
	v_exp_f32_e32 v139, v59
	v_exp_f32_e32 v133, v75
	v_exp_f32_e32 v126, v60
	v_exp_f32_e32 v120, v76
	v_exp_f32_e32 v127, v61
	v_exp_f32_e32 v121, v77
	v_exp_f32_e32 v130, v62
	v_exp_f32_e32 v124, v78
	v_exp_f32_e32 v131, v63
	v_exp_f32_e32 v125, v79
	v_cvt_pk_bf16_f32 v48, v122, v123
	v_cvt_pk_bf16_f32 v49, v132, v133
	v_cvt_pk_bf16_f32 v50, v120, v121
	v_cvt_pk_bf16_f32 v51, v124, v125
	v_cvt_pk_bf16_f32 v52, v136, v137
	v_cvt_pk_bf16_f32 v53, v146, v147
	v_cvt_pk_bf16_f32 v54, v128, v129
	v_cvt_pk_bf16_f32 v55, v140, v141
	v_cvt_pk_bf16_f32 v56, v134, v135
	v_cvt_pk_bf16_f32 v57, v138, v139
	v_cvt_pk_bf16_f32 v58, v126, v127
	v_cvt_pk_bf16_f32 v59, v130, v131
	v_cvt_pk_bf16_f32 v60, v150, v151
	v_cvt_pk_bf16_f32 v61, v148, v149
	v_cvt_pk_bf16_f32 v62, v142, v143
	v_cvt_pk_bf16_f32 v63, v144, v145
	s_setprio 1
	s_waitcnt lgkmcnt(14)
	v_mfma_f32_32x32x16_bf16 v[0:15], v[60:63], v[158:161], v[0:15]
	s_waitcnt lgkmcnt(10)
	v_mfma_f32_32x32x16_bf16 v[16:31], v[60:63], v[166:169], v[16:31]
	v_mfma_f32_32x32x16_bf16 v[0:15], v[56:59], v[162:165], v[0:15]
	s_waitcnt lgkmcnt(8)
	v_mfma_f32_32x32x16_bf16 v[16:31], v[56:59], v[170:173], v[16:31]
	s_waitcnt lgkmcnt(6)
	v_mfma_f32_32x32x16_bf16 v[0:15], v[52:55], v[174:177], v[0:15]
	s_waitcnt lgkmcnt(2)
	v_mfma_f32_32x32x16_bf16 v[16:31], v[52:55], v[184:187], v[16:31]
	v_mfma_f32_32x32x16_bf16 v[0:15], v[48:51], v[180:183], v[0:15]
	s_waitcnt lgkmcnt(0)
	v_mfma_f32_32x32x16_bf16 v[16:31], v[48:51], v[188:191], v[16:31]
	s_setprio 0
	s_cmpk_lt_u32 s12, 0x7d
	s_cbranch_scc0 .Lata_mid_last
	s_waitcnt vmcnt(3)
	ds_write_b128 v155, v[102:105] offset:17408
	s_waitcnt vmcnt(2)
	ds_write_b128 v156, v[110:113] offset:26624
	v_add_co_u32_e32 v48, vcc, 0xffbfc000, v114
	s_nop 1
	v_addc_co_u32_e32 v49, vcc, -1, v115, vcc
	v_add_co_u32_e32 v50, vcc, 0xffffc000, v114
	s_nop 1
	v_addc_co_u32_e32 v51, vcc, -1, v115, vcc
	global_load_dwordx4 v[102:105], v[48:49], off
	global_load_dwordx4 v[110:113], v[50:51], off
	s_branch .LBB0_849
.Lata_mid_last:
	s_waitcnt vmcnt(1)
	ds_write_b128 v155, v[102:105] offset:17408
	s_waitcnt vmcnt(0)
	ds_write_b128 v156, v[110:113] offset:26624
; __device__ __forceinline__ void at_qk(f32x16& p0, f32x16& p1, const bf16_t* Ks, const bf16x8* qr, int r32, int hi) {
;     bf16x8 kf[8];
; #pragma unroll
;     for (int ds = 0; ds < 4; ++ds) {
;         kf[2 * ds] = *(const bf16x8*)(Ks + r32 * 72 + ds * 16 + hi * 8);
;         kf[2 * ds + 1] = *(const bf16x8*)(Ks + (r32 + 32) * 72 + ds * 16 + hi * 8);
;     }
;     __builtin_amdgcn_sched_barrier(0);
;     __builtin_amdgcn_s_setprio(1);
; #pragma unroll
;     for (int ds = 0; ds < 4; ++ds) {
;         p0 = __builtin_amdgcn_mfma_f32_32x32x16_bf16(kf[2 * ds], qr[ds], p0, 0, 0, 0);
;         p1 = __builtin_amdgcn_mfma_f32_32x32x16_bf16(kf[2 * ds + 1], qr[ds], p1, 0, 0, 0);
;     }
;     __builtin_amdgcn_s_setprio(0);
;     __builtin_amdgcn_sched_barrier(0);
; }
; __device__ __forceinline__ void at_pv(f32x16& o0, f32x16& o1, const f32x16& p0, const f32x16& p1, const unsigned char* Vs, int lane) {
;     const int hi = lane >> 5;
;     const unsigned char* vb = Vs + ((lane >> 4) & 1) * 32 + (lane & 3) * 8 + (4 * hi + ((lane & 15) >> 2)) * 64;
;     bf16x8 v0[4], v1[4], pa[4];
; #pragma unroll
;     for (int s = 0; s < 4; ++s) {
;         v0[s] = cat8(tr16(vb + s * 1024), tr16(vb + s * 1024 + 512));
;         v1[s] = cat8(tr16(vb + 4096 + s * 1024), tr16(vb + 4096 + s * 1024 + 512));
;     }
; #pragma unroll
;     for (int s = 0; s < 4; ++s) {
;         u32x4 pw;
;         if (s < 2) { pw.x = pk2(p0[8 * s + 0], p0[8 * s + 1]); pw.y = pk2(p0[8 * s + 2], p0[8 * s + 3]); pw.z = pk2(p0[8 * s + 4], p0[8 * s + 5]); pw.w = pk2(p0[8 * s + 6], p0[8 * s + 7]); }
;         else { const int q = s - 2; pw.x = pk2(p1[8 * q + 0], p1[8 * q + 1]); pw.y = pk2(p1[8 * q + 2], p1[8 * q + 3]); pw.z = pk2(p1[8 * q + 4], p1[8 * q + 5]); pw.w = pk2(p1[8 * q + 6], p1[8 * q + 7]); }
;         pa[s] = __builtin_bit_cast(bf16x8, pw);
;     }
;     __builtin_amdgcn_sched_barrier(0);
;     __builtin_amdgcn_s_setprio(1);
; #pragma unroll
; __device__ void attn_a_item(const Params& p, int item, int l, unsigned char* smem) {
;     ...
;     for (int kt = 0; kt < NT; kt += 2) {
;         ATA_COMPUTE(0);
;         ATA_STORE(rkB, rvB, 1);
;         if (kt + 3 < NT) ATA_LOAD(rkB, rvB, kt + 3);
;         __syncthreads();
;         ATA_COMPUTE(1);
;         if (kt + 2 < NT) { ATA_STORE(rkA, rvA, 0); if (kt + 4 < NT) ATA_LOAD(rkA, rvA, kt + 4); }
;         __syncthreads();
;     }
.LBB0_849:
	s_waitcnt lgkmcnt(0)
	s_barrier
	ds_read_b128 v[48:51], v80 offset:17408
	ds_read_b128 v[158:161], v80 offset:17440
	ds_read_b128 v[162:165], v80 offset:22016
	ds_read_b128 v[166:169], v80 offset:22048
	ds_read_b128 v[170:173], v80 offset:17472
	ds_read_b128 v[174:177], v80 offset:17504
	ds_read_b128 v[180:183], v80 offset:22080
	ds_read_b128 v[184:187], v80 offset:22112
	s_setprio 1
	s_waitcnt lgkmcnt(7)
	v_mfma_f32_32x32x16_bf16 v[64:79], v[48:51], v[82:85], v[32:47]
	s_waitcnt lgkmcnt(5)
	v_mfma_f32_32x32x16_bf16 v[48:63], v[162:165], v[82:85], v[32:47]
	v_mfma_f32_32x32x16_bf16 v[64:79], v[158:161], v[86:89], v[64:79]
	s_waitcnt lgkmcnt(4)
	v_mfma_f32_32x32x16_bf16 v[48:63], v[166:169], v[86:89], v[48:63]
	s_waitcnt lgkmcnt(3)
	v_mfma_f32_32x32x16_bf16 v[64:79], v[170:173], v[90:93], v[64:79]
	s_waitcnt lgkmcnt(1)
	v_mfma_f32_32x32x16_bf16 v[48:63], v[180:183], v[90:93], v[48:63]
	v_mfma_f32_32x32x16_bf16 v[64:79], v[174:177], v[94:97], v[64:79]
	s_waitcnt lgkmcnt(0)
	v_mfma_f32_32x32x16_bf16 v[48:63], v[184:187], v[94:97], v[48:63]
	s_setprio 0
	ds_read_b64_tr_b16 v[158:159], v157 offset:26624
	ds_read_b64_tr_b16 v[160:161], v157 offset:27136
	ds_read_b64_tr_b16 v[162:163], v157 offset:27648
	ds_read_b64_tr_b16 v[164:165], v157 offset:28160
	ds_read_b64_tr_b16 v[166:167], v157 offset:30720
	ds_read_b64_tr_b16 v[168:169], v157 offset:31232
	ds_read_b64_tr_b16 v[170:171], v157 offset:31744
	ds_read_b64_tr_b16 v[172:173], v157 offset:32256
	ds_read_b64_tr_b16 v[174:175], v157 offset:28672
	ds_read_b64_tr_b16 v[176:177], v157 offset:29184
	ds_read_b64_tr_b16 v[180:181], v157 offset:29696
	ds_read_b64_tr_b16 v[182:183], v157 offset:30208
	ds_read_b64_tr_b16 v[184:185], v157 offset:32768
	ds_read_b64_tr_b16 v[186:187], v157 offset:33280
	ds_read_b64_tr_b16 v[188:189], v157 offset:33792
	ds_read_b64_tr_b16 v[190:191], v157 offset:34304
	v_exp_f32_e32 v64, v64
	v_exp_f32_e32 v48, v48
	v_exp_f32_e32 v65, v65
	v_exp_f32_e32 v49, v49
	v_exp_f32_e32 v66, v66
	v_exp_f32_e32 v50, v50
	v_exp_f32_e32 v67, v67
	v_exp_f32_e32 v51, v51
	v_exp_f32_e32 v68, v68
	v_exp_f32_e32 v52, v52
	v_exp_f32_e32 v69, v69
	v_exp_f32_e32 v53, v53
	v_exp_f32_e32 v70, v70
	v_exp_f32_e32 v54, v54
	v_exp_f32_e32 v71, v71
	v_exp_f32_e32 v55, v55
	v_exp_f32_e32 v72, v72
	v_exp_f32_e32 v56, v56
	v_exp_f32_e32 v73, v73
	v_exp_f32_e32 v57, v57
	v_exp_f32_e32 v74, v74
	v_exp_f32_e32 v58, v58
	v_exp_f32_e32 v75, v75
	v_exp_f32_e32 v59, v59
	v_exp_f32_e32 v76, v76
	v_exp_f32_e32 v60, v60
	v_exp_f32_e32 v77, v77
	v_exp_f32_e32 v61, v61
	v_exp_f32_e32 v78, v78
	v_exp_f32_e32 v62, v62
	v_exp_f32_e32 v79, v79
	v_exp_f32_e32 v63, v63
	v_cvt_pk_bf16_f32 v192, v56, v57
	v_cvt_pk_bf16_f32 v193, v58, v59
	v_cvt_pk_bf16_f32 v194, v60, v61
	v_cvt_pk_bf16_f32 v195, v62, v63
	v_cvt_pk_bf16_f32 v196, v48, v49
	v_cvt_pk_bf16_f32 v197, v50, v51
	v_cvt_pk_bf16_f32 v198, v52, v53
	v_cvt_pk_bf16_f32 v199, v54, v55
	v_cvt_pk_bf16_f32 v200, v72, v73
	v_cvt_pk_bf16_f32 v201, v74, v75
	v_cvt_pk_bf16_f32 v202, v76, v77
	v_cvt_pk_bf16_f32 v203, v78, v79
	v_cvt_pk_bf16_f32 v204, v64, v65
	v_cvt_pk_bf16_f32 v205, v66, v67
	v_cvt_pk_bf16_f32 v206, v68, v69
	v_cvt_pk_bf16_f32 v207, v70, v71
	s_setprio 1
	s_waitcnt lgkmcnt(14)
	v_mfma_f32_32x32x16_bf16 v[0:15], v[204:207], v[158:161], v[0:15]
	s_waitcnt lgkmcnt(10)
	v_mfma_f32_32x32x16_bf16 v[16:31], v[204:207], v[166:169], v[16:31]
	v_mfma_f32_32x32x16_bf16 v[0:15], v[200:203], v[162:165], v[0:15]
	s_waitcnt lgkmcnt(8)
	v_mfma_f32_32x32x16_bf16 v[16:31], v[200:203], v[170:173], v[16:31]
	s_waitcnt lgkmcnt(6)
	v_mfma_f32_32x32x16_bf16 v[0:15], v[196:199], v[174:177], v[0:15]
	s_waitcnt lgkmcnt(2)
	v_mfma_f32_32x32x16_bf16 v[16:31], v[196:199], v[184:187], v[16:31]
	v_mfma_f32_32x32x16_bf16 v[0:15], v[192:195], v[180:183], v[0:15]
	s_waitcnt lgkmcnt(0)
	v_mfma_f32_32x32x16_bf16 v[16:31], v[192:195], v[188:191], v[16:31]
	s_setprio 0
	s_cmpk_gt_u32 s12, 0x7d
	s_cselect_b64 s[44:45], -1, 0
	s_and_b64 vcc, exec, s[44:45]
	s_cbranch_vccnz .LBB0_846
	s_cmpk_gt_u32 s12, 0x7b
	s_waitcnt vmcnt(3)
	ds_write_b128 v155, v[98:101]
	s_waitcnt vmcnt(2)
	ds_write_b128 v156, v[106:109] offset:9216
	s_cbranch_scc1 .LBB0_846
	v_add_co_u32_e32 v98, vcc, 0xffc00000, v114
	s_nop 1
	v_addc_co_u32_e32 v99, vcc, -1, v115, vcc
	global_load_dwordx4 v[98:101], v[98:99], off
	s_nop 0
	global_load_dwordx4 v[106:109], v[114:115], off
	s_branch .LBB0_846
